# filler ranges rebalanced after the faster K loop: 1280 W_up0 conversion jobs move from phase 1 to the idle workgroups of phase 3
# baseline (speedup 1.0000x reference)
.LBB0_731:
	s_cmp_eq_u32 s28, 3
	s_cbranch_scc1 .Lfx_ph3
	s_cmp_eq_u32 s28, 6
	s_cbranch_scc1 .Lfx_ph6
	s_andn2_b64 vcc, exec, s[6:7]
	s_cbranch_vccnz .LBB0_804
	s_cmp_eq_u32 s28, 9
	s_movk_i32 s6, 0x7000
	s_mov_b32 s7, 0xb000
	s_cselect_b32 s6, s6, 0x9000
	s_cselect_b32 s7, 0x9000, s7
	s_movk_i32 s30, 0x4000
	s_movk_i32 s34, 0x7000
	s_cmpk_eq_i32 s3, 0x100
	s_cselect_b32 s30, 0x4a00, s30
	s_cselect_b32 s34, 0x6c00, s34
	s_cmp_eq_u32 s28, 5
	s_cselect_b32 s8, s30, s6
	s_cselect_b32 s9, s34, s7
	s_movk_i32 s12, 0x4000
	s_cmpk_eq_i32 s3, 0x100
	s_cselect_b32 s12, 0x3b00, s12
	s_and_b64 s[6:7], exec, s[36:37]
	s_cselect_b32 s30, 0x1800, s8
	s_cselect_b32 s34, s12, s9
	s_branch .Lfx_go
.Lfx_ph3:
	s_movk_i32 s30, 0x3b00
	s_movk_i32 s34, 0x4a00
	s_movk_i32 s83, 0x60
	s_branch .Lfx_chk
